# P0 small-parameter tasks spread over different workgroups (shorter serial chain before first grid barrier)
# speedup vs baseline: 1.0067x; 1.0067x over previous
.LBB0_149:
	s_or_b64 exec, exec, s[0:1]
	s_cmpk_eq_i32 s33, 0x100
	s_cselect_b32 s3, 0x2000, 0
	v_subrev_u32_e32 v8, s3, v8
	s_movk_i32 s0, 0xe88
	v_cmp_gt_u32_e32 vcc, s0, v8
	s_and_saveexec_b64 s[0:1], vcc
	s_cbranch_execz .LBB0_152
	s_ashr_i32 s13, s12, 31
	s_lshl_b64 s[6:7], s[12:13], 2
	s_add_u32 s14, s28, 0x785800
	v_lshlrev_b64 v[4:5], 2, v[8:9]
	s_addc_u32 s15, s29, 0
	s_mov_b64 s[16:17], 0
	s_movk_i32 s3, 0xe87
	v_mov_b32_e32 v1, v8

.LBB0_152:
	s_or_b64 exec, exec, s[0:1]
	s_cmpk_eq_i32 s33, 0x100
	s_cselect_b32 s3, 0x2000, 0
	v_subrev_u32_e32 v8, s3, v8
	s_movk_i32 s0, 0x1000
	v_cmp_gt_u32_e32 vcc, s0, v8
	s_and_saveexec_b64 s[6:7], vcc
	s_cbranch_execz .LBB0_155
	s_ashr_i32 s13, s12, 31
	s_lshl_b64 s[14:15], s[12:13], 2
	s_add_u32 s16, s28, 0x789240
	v_lshlrev_b64 v[4:5], 2, v[8:9]
	s_addc_u32 s17, s29, 0
	s_mov_b64 s[18:19], 0
	s_movk_i32 s3, 0xfff
	v_mov_b32_e32 v1, v8

.LBB0_155:
	s_or_b64 exec, exec, s[6:7]
	s_cmpk_eq_i32 s33, 0x100
	s_cselect_b32 s3, 0x2000, 0
	v_subrev_u32_e32 v8, s3, v8
	s_movk_i32 s0, 0x400
	v_cmp_gt_u32_e64 s[6:7], s0, v8
	s_and_saveexec_b64 s[14:15], s[6:7]
	s_cbranch_execz .LBB0_158
	s_ashr_i32 s13, s12, 31
	s_lshl_b64 s[16:17], s[12:13], 2
	s_add_u32 s18, s28, 0x78d240
	v_lshlrev_b64 v[4:5], 2, v[8:9]
	s_addc_u32 s19, s29, 0
	s_mov_b64 s[20:21], 0
	s_movk_i32 s3, 0x3ff
	v_mov_b32_e32 v1, v8

.LBB0_158:
	s_or_b64 exec, exec, s[14:15]
	s_cmpk_eq_i32 s33, 0x100
	s_cselect_b32 s3, 0x1000, 0
	v_subrev_u32_e32 v8, s3, v8
	s_movk_i32 s0, 0x800
	v_cmp_gt_u32_e64 s[0:1], s0, v8
	s_and_saveexec_b64 s[14:15], s[0:1]
	s_cbranch_execz .LBB0_165
	s_ashr_i32 s13, s12, 31
	s_lshl_b64 s[16:17], s[12:13], 2
	v_lshlrev_b64 v[4:5], 2, v[8:9]
	s_add_u32 s18, s28, 0x78e240
	s_addc_u32 s19, s29, 0
	s_mov_b64 s[20:21], 0
	s_movk_i32 s3, 0x7ff
	v_mov_b64_e32 v[6:7], v[4:5]
	v_mov_b32_e32 v1, v8

.LBB0_165:
	s_or_b64 exec, exec, s[14:15]
	s_cmpk_eq_i32 s33, 0x100
	s_cselect_b32 s3, 0x1000, 0
	v_add_u32_e32 v8, s3, v8
	s_and_saveexec_b64 s[14:15], s[6:7]
	s_cbranch_execz .LBB0_168
	s_ashr_i32 s13, s12, 31
	s_lshl_b64 s[6:7], s[12:13], 2
	s_add_u32 s16, s28, 0x794240
	v_lshlrev_b64 v[4:5], 2, v[8:9]
	s_addc_u32 s17, s29, 0
	s_mov_b64 s[18:19], 0
	s_movk_i32 s3, 0x3ff
	v_mov_b32_e32 v1, v8

.LBB0_168:
	s_or_b64 exec, exec, s[14:15]
	s_waitcnt lgkmcnt(0)
	s_add_u32 s42, s28, 0x4800000
	s_addc_u32 s43, s29, 0
	v_and_b32_e32 v197, 7, v156
	s_cmpk_eq_i32 s33, 0x100
	s_cselect_b32 s3, 0x2000, 0
	v_add_u32_e32 v8, s3, v8
	s_and_saveexec_b64 s[0:1], vcc
	s_cbranch_execz .LBB0_171
	v_lshlrev_b32_e32 v4, 4, v197
	v_mov_b32_e32 v5, 0
	v_lshl_add_u64 v[10:11], s[42:43], 0, v[4:5]
	s_mov_b64 s[6:7], 0
	s_movk_i32 s3, 0x804
	v_mov_b32_e32 v4, v5
	v_mov_b32_e32 v6, v5
	v_mov_b32_e32 v7, v5
	s_movk_i32 s4, 0xfff
	s_waitcnt vmcnt(0)

.LBB0_171:
	s_or_b64 exec, exec, s[0:1]
	s_cmpk_eq_i32 s33, 0x100
	s_cselect_b32 s4, 0x200, 0
	s_sub_i32 s4, s76, s4
	s_cmpk_gt_u32 s4, 0x1ff
	s_cbranch_scc1 .LBB0_176
	v_mbcnt_lo_u32_b32 v1, -1, 0
	v_mbcnt_hi_u32_b32 v5, -1, v1
	v_and_b32_e32 v3, 64, v5
	v_xor_b32_e32 v1, 8, v5
	v_add_u32_e32 v6, 64, v3
	v_cmp_lt_i32_e32 vcc, v1, v6
	v_xor_b32_e32 v3, 16, v5
	v_and_b32_e32 v4, 56, v156
	v_cndmask_b32_e32 v1, v5, v1, vcc
	v_cmp_lt_i32_e32 vcc, v3, v6
	v_xor_b32_e32 v7, 32, v5
	s_waitcnt vmcnt(2)
	v_or_b32_e32 v26, 7, v157
	v_cndmask_b32_e32 v3, v5, v3, vcc
	v_cmp_lt_i32_e32 vcc, v7, v6
	v_lshlrev_b32_e32 v6, 6, v4
	s_lshl_b32 s0, s84, 6
	s_lshl_b32 s1, s86, 3
	v_cndmask_b32_e32 v5, v5, v7, vcc
	v_mov_b32_e32 v7, 0
	v_or_b32_e32 v12, 64, v6
	v_or_b32_e32 v14, 0x80, v6
	v_or_b32_e32 v16, 0xc0, v6
	v_or_b32_e32 v18, 0x100, v6
	v_or_b32_e32 v20, 0x140, v6
	v_or_b32_e32 v22, 0x180, v6
	v_lshlrev_b32_e32 v24, 6, v26
	s_lshl_b32 s0, s4, 3
	v_lshlrev_b32_e32 v1, 2, v1
	v_lshlrev_b32_e32 v3, 2, v3
	v_lshlrev_b32_e32 v5, 2, v5
	v_cmp_gt_u32_e64 s[6:7], 8, v157
	v_and_or_b32 v8, v156, 7, s0
	s_lshl_b32 s3, s33, 6
	v_lshlrev_b32_e32 v10, 2, v6
	v_mov_b32_e32 v11, v7
	v_lshlrev_b32_e32 v12, 2, v12
	v_mov_b32_e32 v13, v7
	v_lshlrev_b32_e32 v14, 2, v14
	v_mov_b32_e32 v15, v7
	v_lshlrev_b32_e32 v16, 2, v16
	v_mov_b32_e32 v17, v7
	v_lshlrev_b32_e32 v18, 2, v18
	v_mov_b32_e32 v19, v7
	v_lshlrev_b32_e32 v20, 2, v20
	v_mov_b32_e32 v21, v7
	v_lshlrev_b32_e32 v22, 2, v22
	v_mov_b32_e32 v23, v7
	v_lshlrev_b32_e32 v24, 2, v24
	v_mov_b32_e32 v25, v7
	s_branch .LBB0_174
